# conv_mix_unit: 8 row loads issued up front, edge rows of waves 0 and 7 both in the first block (waves 4-7 walk blocks in reverse)
# speedup vs baseline: 1.0004x; 1.0004x over previous
; __device__ __forceinline__ void conv_mix_unit(const bf16_t* Z, bf16_t* mix, const float* E2, const float* cw, const float* cbias, long row0, int h, int t0, int S, int tid) {
;     const int pm = (int)(row0 >> 8);
; #pragma unroll
;     for (int it = 0; it < 4; ++it) {
;         const int idx = tid + 512 * it, r = idx >> 3, ch = h * 64 + (idx & 7) * 8; const size_t row = (size_t)row0 + r;
;         float fb[8], cp[8];
;         unpack8(*(const u32x4*)(Z + row * INW + 768 + ch), fb);
;         if (r == 0 || r == 255) {
.LBB0_287:
	s_waitcnt lgkmcnt(0)
	s_add_u32 s12, s20, 0xe000000
	s_addc_u32 s13, s21, 0
	s_add_u32 s14, s20, 0x20000000
	s_addc_u32 s15, s21, 0
	s_add_u32 s16, s20, 0x100000
	s_addc_u32 s17, s21, 0
	s_add_u32 s18, s20, 0x2b100000
	s_addc_u32 s19, s21, 0
	s_load_dwordx2 s[0:1], s[54:55], 0x18
	s_add_u32 s6, s20, 0xe000400
	s_addc_u32 s7, s21, 0
	s_add_u32 s56, s20, 0xe000500
	s_addc_u32 s57, s21, 0
	s_lshl_b64 s[4:5], s[26:27], 2
	s_waitcnt lgkmcnt(0)
	s_add_u32 s20, s0, s4
	v_mov_b32_e32 v96, 0x200
	v_mov_b32_e32 v97, 0xfffffe00
	v_add_u32_e32 v98, 0x600, v0
	v_cmp_lt_u32_e32 vcc, 255, v0
	s_nop 1
	v_cndmask_b32_e32 v96, v96, v97, vcc
	v_cndmask_b32_e32 v0, v0, v98, vcc
	v_lshlrev_b32_e32 v1, 3, v0
	v_ashrrev_i32_e32 v194, 3, v0
	s_movk_i32 s0, 0xff
	v_and_b32_e32 v242, 56, v1
	v_cmp_lt_u32_e32 vcc, 7, v0
	v_cmp_ne_u32_e64 s[40:41], s0, v194
	v_add_u32_e32 v1, v96, v0
	s_addc_u32 s21, s1, s5
	s_and_b64 s[22:23], vcc, s[40:41]
	v_cmp_eq_u32_e32 vcc, s0, v194
	v_mov_b32_e32 v2, 0xfffff800
	v_mov_b32_e32 v3, 0x1000
	v_mov_b32_e32 v4, 0x1800
	v_mov_b32_e32 v5, 0x800
	v_mov_b32_e32 v6, 0x2000
	v_ashrrev_i32_e32 v202, 3, v1
	v_cndmask_b32_e64 v197, -1, 0, vcc
	v_cndmask_b32_e32 v196, v2, v3, vcc
	v_cndmask_b32_e32 v198, 0, v4, vcc
	v_cndmask_b32_e32 v200, v5, v6, vcc
	v_cmp_lt_u32_e32 vcc, 7, v1
	v_cmp_ne_u32_e64 s[40:41], s0, v202
	v_lshl_add_u32 v1, v96, 1, v0
	s_and_b64 s[24:25], vcc, s[40:41]
	v_cmp_eq_u32_e32 vcc, s0, v202
	v_ashrrev_i32_e32 v210, 3, v1
	v_cmp_ne_u32_e64 s[40:41], s0, v210
	v_cndmask_b32_e64 v205, -1, 0, vcc
	v_cndmask_b32_e32 v204, v2, v3, vcc
	v_cndmask_b32_e32 v206, 0, v4, vcc
	v_cndmask_b32_e32 v208, v5, v6, vcc
	v_cmp_lt_u32_e32 vcc, 7, v1
	v_lshl_add_u32 v0, v96, 1, v0
	v_add_u32_e32 v0, v96, v0
	s_and_b64 s[26:27], vcc, s[40:41]
	v_cmp_eq_u32_e32 vcc, s0, v210
	v_ashrrev_i32_e32 v218, 3, v0
	v_cmp_ne_u32_e64 s[40:41], s0, v218
	v_cndmask_b32_e64 v213, -1, 0, vcc
	v_cndmask_b32_e32 v212, v2, v3, vcc
	v_cndmask_b32_e32 v214, 0, v4, vcc
	v_cndmask_b32_e32 v216, v5, v6, vcc
	v_cmp_lt_u32_e32 vcc, 7, v0
	s_and_b64 s[28:29], vcc, s[40:41]
	v_cmp_eq_u32_e32 vcc, s0, v218
	v_ashrrev_i32_e32 v195, 31, v194
	s_mov_b32 s60, 0
	v_mov_b32_e32 v199, v189
	v_mov_b32_e32 v201, v189
	v_ashrrev_i32_e32 v203, 31, v202
	v_mov_b32_e32 v207, v189
	v_mov_b32_e32 v209, v189
	v_ashrrev_i32_e32 v211, 31, v210
	v_mov_b32_e32 v215, v189
	v_mov_b32_e32 v217, v189
	v_ashrrev_i32_e32 v219, 31, v218
	v_cndmask_b32_e64 v221, -1, 0, vcc
	v_cndmask_b32_e32 v220, v2, v3, vcc
	v_cndmask_b32_e32 v222, 0, v4, vcc
	v_mov_b32_e32 v223, v189
	v_cndmask_b32_e32 v224, v5, v6, vcc
	v_mov_b32_e32 v225, v189
	s_branch .LBB0_290

; __device__ __forceinline__ unsigned pk(float lo, float hi) { return pg8::cvt_pk_bf16(lo, hi); }
; __device__ __forceinline__ void conv_mix_unit(const bf16_t* Z, bf16_t* mix, const float* E2, const float* cw, const float* cbias, long row0, int h, int t0, int S, int tid) {
;     ...
;         const int idx = tid + 512 * it, r = idx >> 3, ch = h * 64 + (idx & 7) * 8; const size_t row = (size_t)row0 + r;
;         float fb[8], cp[8];
;         unpack8(*(const u32x4*)(Z + row * INW + 768 + ch), fb);
;         if (r == 0 || r == 255) {
;             const float* Ep = E2 + (size_t)pm * 4 * 512 + ch; const bool last = r == 255;
;             const float* r0 = last ? Ep + 2 * 512 : Ep - 512; const float* r1 = last ? Ep + 3 * 512 : Ep; const float* r2 = last ? Ep + 4 * 512 : Ep + 512;
;             const bool hasp = t0 + r > 0, hasn = t0 + r < S - 1;
; #pragma unroll
;             for (int i = 0; i < 8; ++i) cp[i] = cw[ch + i] * (hasp ? r0[i] : 0.f) + cw[512 + ch + i] * r1[i] + cw[1024 + ch + i] * (hasn ? r2[i] : 0.f) + cbias[ch + i];
;         } else unpack8(*(const u32x4*)(Z + row * INW + 1280 + ch), cp);
;         u32x4 w; w.x = pk(fb[0] * cp[0], fb[1] * cp[1]); w.y = pk(fb[2] * cp[2], fb[3] * cp[3]); w.z = pk(fb[4] * cp[4], fb[5] * cp[5]); w.w = pk(fb[6] * cp[6], fb[7] * cp[7]);
;         *(u32x4*)(mix + row * DM + 512 + ch) = w;
.LBB0_289:
	s_or_b64 exec, exec, s[30:31]
	v_and_b32_e32 v15, 0xffff0000, v124
	v_lshlrev_b32_e32 v8, 16, v124
	v_and_b32_e32 v14, 0xffff0000, v125
	v_lshlrev_b32_e32 v9, 16, v125
	v_mul_f32_e32 v0, v0, v8
	v_mul_f32_e32 v1, v1, v15
	v_and_b32_e32 v13, 0xffff0000, v126
	v_lshlrev_b32_e32 v10, 16, v126
	v_cvt_pk_bf16_f32 v0, v0, v1
	v_mul_f32_e32 v1, v2, v9
	v_mul_f32_e32 v2, v3, v14
	v_and_b32_e32 v12, 0xffff0000, v127
	v_lshlrev_b32_e32 v11, 16, v127
	v_cvt_pk_bf16_f32 v1, v1, v2
	v_mul_f32_e32 v2, v4, v10
	v_mul_f32_e32 v3, v5, v13
	v_cvt_pk_bf16_f32 v2, v2, v3
	v_mul_f32_e32 v3, v6, v11
	v_mul_f32_e32 v4, v7, v12
	v_cvt_pk_bf16_f32 v3, v3, v4
	v_lshlrev_b64 v[4:5], 11, v[18:19]
	v_lshl_add_u64 v[4:5], s[14:15], 0, v[4:5]
	v_mov_b32_e32 v17, v189
	s_add_i32 s60, s60, 1
	v_lshl_add_u64 v[4:5], v[4:5], 0, v[16:17]
	s_cmp_eq_u32 s60, 8
	global_store_dwordx4 v[4:5], v[0:3], off offset:1024
	s_cbranch_scc1 .LBB0_507

; __device__ __forceinline__ int crow(int r,int hi){return (r&3)+8*(r>>2)+4*hi;}
; #define SBAR() __builtin_amdgcn_sched_barrier(0)
;   #define RESC() do{ if(resc){ asm volatile("s_waitcnt lgkmcnt(0)":::"memory"); \
;       _Pragma("unroll") for(int d_=0;d_<2;++d_) _Pragma("unroll") for(int r=0;r<16;++r)o[d_][r]*=wsf[crow(r,hi)]; } }while(0)
;   #define PKW(P,B) cvtpk_s(P[B],P[B+1])
; template<int THRL> __device__ __forceinline__ void attn_unit(long rowbase,int NT,int q0,const bf16*Qh,const bf16*Kc,const bf16*Vc,bf16*Oh,char*shm,const float*rope,const float*qn){
;     ...
;   STEP(pB0,pB1,pA0,pA1,NT-1,false,false,false); RESC();
;   { float sacc=pB0[0]+pB0[1]; _Pragma("unroll") for(int r=2;r<16;++r)sacc+=pB0[r]; _Pragma("unroll") for(int r=0;r<16;++r)sacc+=pB1[r]; l_reg+=sacc;
;     pw0=(u32x4){PKW(pB0,0),PKW(pB0,2),PKW(pB0,4),PKW(pB0,6)};pw1=(u32x4){PKW(pB0,8),PKW(pB0,10),PKW(pB0,12),PKW(pB0,14)};pw2=(u32x4){PKW(pB1,0),PKW(pB1,2),PKW(pB1,4),PKW(pB1,6)};pw3=(u32x4){PKW(pB1,8),PKW(pB1,10),PKW(pB1,12),PKW(pB1,14)};
;     SBAR(); pv(o,vb0+sl_cur,PAF(0),PAF(1),PAF(2),PAF(3)); }
;     ...
;   {auto rr=__builtin_amdgcn_permlane32_swap(__float_as_uint(l_reg),__float_as_uint(l_reg),false,false);l_reg=__uint_as_float(rr[0])+__uint_as_float(rr[1]);}
;   if(hi==0)wsf[32+r32]=l_reg;asm volatile("s_waitcnt lgkmcnt(0)":::"memory");
;   float rli[16];
;   #pragma unroll
;   for(int r=0;r<16;++r)rli[r]=__builtin_amdgcn_rcpf(wsf[32+crow(r,hi)]);
;   bf16*Ow=Oh+(rowbase+q0+wid*QBLK)*PO;
;   { bf16*stg=(bf16*)(shm+LDS_OST)+wid*2048;
;     #pragma unroll
;     for(int r=0;r<16;++r){const int orow=crow(r,hi);
;       #pragma unroll
;       for(int d0=0;d0<2;++d0)stg[orow*64+d0*32+r32]=__float2bfloat16(o[d0][r]*rli[r]);}
.LBB0_359:
	v_add_f32_e32 v48, v80, v81
	v_add_f32_e32 v48, v82, v48
	v_add_f32_e32 v48, v83, v48
	v_add_f32_e32 v48, v84, v48
	v_add_f32_e32 v48, v85, v48
	v_add_f32_e32 v48, v86, v48
	v_add_f32_e32 v48, v87, v48
	v_add_f32_e32 v48, v88, v48
	v_add_f32_e32 v48, v89, v48
	v_add_f32_e32 v48, v90, v48
	v_add_f32_e32 v48, v91, v48
	v_add_f32_e32 v48, v92, v48
	v_add_f32_e32 v48, v93, v48
	v_add_f32_e32 v48, v94, v48
	v_add_f32_e32 v48, v95, v48
	v_add_f32_e32 v48, v32, v48
	v_add_f32_e32 v48, v33, v48
	v_add_f32_e32 v48, v34, v48
	v_add_f32_e32 v48, v35, v48
	v_add_f32_e32 v48, v36, v48
	v_add_f32_e32 v48, v37, v48
	v_add_f32_e32 v48, v38, v48
	v_add_f32_e32 v48, v39, v48
	v_add_f32_e32 v48, v40, v48
	v_add_f32_e32 v48, v41, v48
	v_add_f32_e32 v48, v42, v48
	v_add_f32_e32 v48, v43, v48
	v_add_f32_e32 v48, v44, v48
	v_add_f32_e32 v48, v45, v48
	s_cmp_lg_u32 0, -1
	v_add_f32_e32 v48, v46, v48
	s_cselect_b32 s0, 0, 0
	v_add_f32_e32 v48, v47, v48
	s_addk_i32 s0, 0x6000
	v_add_f32_e32 v48, v112, v48
	v_cvt_pk_bf16_f32 v32, v32, v33
	v_add3_u32 v49, v248, s0, v247
	v_cvt_pk_bf16_f32 v50, v80, v81
	v_cvt_pk_bf16_f32 v51, v82, v83
	v_cvt_pk_bf16_f32 v52, v84, v85
	v_cvt_pk_bf16_f32 v53, v86, v87
	v_cvt_pk_bf16_f32 v54, v88, v89
	v_cvt_pk_bf16_f32 v55, v90, v91
	v_cvt_pk_bf16_f32 v56, v92, v93
	v_cvt_pk_bf16_f32 v57, v94, v95
	v_cvt_pk_bf16_f32 v33, v34, v35
	v_cvt_pk_bf16_f32 v34, v36, v37
	v_cvt_pk_bf16_f32 v35, v38, v39
	v_cvt_pk_bf16_f32 v36, v40, v41
	v_cvt_pk_bf16_f32 v37, v42, v43
	v_cvt_pk_bf16_f32 v38, v44, v45
	v_cvt_pk_bf16_f32 v39, v46, v47
	v_add3_u32 v49, v49, v188, s71
	ds_read_b64_tr_b16 v[40:41],v49 offset:0
	ds_read_b64_tr_b16 v[42:43],v49 offset:512
	ds_read_b64_tr_b16 v[44:45],v49 offset:1024
	ds_read_b64_tr_b16 v[46:47],v49 offset:1536
	ds_read_b64_tr_b16 v[58:59],v49 offset:2048
	ds_read_b64_tr_b16 v[60:61],v49 offset:2560
	ds_read_b64_tr_b16 v[62:63],v49 offset:3072
	ds_read_b64_tr_b16 v[64:65],v49 offset:3584
	s_waitcnt lgkmcnt(0)
	s_nop 0
	v_mfma_f32_32x32x16_bf16 v[0:15], v[50:53], v[40:43], v[0:15]
	ds_read_b64_tr_b16 v[40:41],v49 offset:4096
	ds_read_b64_tr_b16 v[42:43],v49 offset:4608
	v_mfma_f32_32x32x16_bf16 v[0:15], v[54:57], v[44:47], v[0:15]
	ds_read_b64_tr_b16 v[44:45],v49 offset:5120
	ds_read_b64_tr_b16 v[46:47],v49 offset:5632
	v_mfma_f32_32x32x16_bf16 v[0:15], v[32:35], v[58:61], v[0:15]
	ds_read_b64_tr_b16 v[58:59],v49 offset:6144
	ds_read_b64_tr_b16 v[60:61],v49 offset:6656
	v_mfma_f32_32x32x16_bf16 v[0:15], v[36:39], v[62:65], v[0:15]
	ds_read_b64_tr_b16 v[62:63],v49 offset:7168
	ds_read_b64_tr_b16 v[64:65],v49 offset:7680
	s_waitcnt lgkmcnt(0)
	v_mfma_f32_32x32x16_bf16 v[16:31], v[50:53], v[40:43], v[16:31]
	v_mfma_f32_32x32x16_bf16 v[16:31], v[54:57], v[44:47], v[16:31]
	v_mfma_f32_32x32x16_bf16 v[16:31], v[32:35], v[58:61], v[16:31]
	v_mov_b32_e32 v32, v48
	s_nop 1
	v_permlane32_swap_b32_e32 v48, v32
	v_mfma_f32_32x32x16_bf16 v[16:31], v[36:39], v[62:65], v[16:31]
	s_and_saveexec_b64 s[0:1], s[40:41]
	v_add_f32_e32 v32, v48, v32
	ds_write_b32 v250, v32 offset:49280
	s_or_b64 exec, exec, s[0:1]
	s_waitcnt lgkmcnt(0)
	ds_read_b128 v[32:35], v249 offset:49280
	ds_read_b128 v[36:39], v249 offset:49312
	s_lshl_b32 s0, s4, 1
	s_add_u32 s0, s14, s0
	s_addc_u32 s1, s15, 0
	s_waitcnt lgkmcnt(1)
	v_rcp_f32_e32 v40, v32
	s_lshl_b32 s5, s5, 12
	v_rcp_f32_e32 v41, v33
	s_add_i32 s5, s5, 0
	v_lshlrev_b32_e32 v48, 1, v245
	v_lshlrev_b32_e32 v49, 9, v246
	v_mul_f32_e32 v0, v0, v40
	v_add3_u32 v48, s5, v48, v49
	v_cvt_pk_bf16_f32 v0, v0, s0
	v_rcp_f32_e32 v42, v34
	v_rcp_f32_e32 v43, v35
	s_waitcnt lgkmcnt(0)
	v_rcp_f32_e32 v44, v36
	ds_read_b128 v[32:35], v249 offset:49344
	v_rcp_f32_e32 v45, v37
	v_rcp_f32_e32 v46, v38
	v_rcp_f32_e32 v47, v39
	ds_read_b128 v[36:39], v249 offset:49376
	ds_write_b16 v48, v0 offset:51200
	v_mul_f32_e32 v0, v16, v40
	v_cvt_pk_bf16_f32 v0, v0, s0
	ds_write_b16 v48, v0 offset:51264
	v_mul_f32_e32 v0, v1, v41
	v_cvt_pk_bf16_f32 v0, v0, s0
	ds_write_b16 v48, v0 offset:51328
	v_mul_f32_e32 v0, v17, v41
	v_cvt_pk_bf16_f32 v0, v0, s0
	ds_write_b16 v48, v0 offset:51392
	v_mul_f32_e32 v0, v2, v42
	v_cvt_pk_bf16_f32 v0, v0, s0
	ds_write_b16 v48, v0 offset:51456
	v_mul_f32_e32 v0, v18, v42
	v_cvt_pk_bf16_f32 v0, v0, s0
	ds_write_b16 v48, v0 offset:51520
	v_mul_f32_e32 v0, v3, v43
	v_cvt_pk_bf16_f32 v0, v0, s0
	ds_write_b16 v48, v0 offset:51584
	v_mul_f32_e32 v0, v19, v43
	v_cvt_pk_bf16_f32 v0, v0, s0
	ds_write_b16 v48, v0 offset:51648
	v_mul_f32_e32 v0, v4, v44
	v_cvt_pk_bf16_f32 v0, v0, s0
	ds_write_b16 v48, v0 offset:52224
	v_mul_f32_e32 v0, v20, v44
	v_cvt_pk_bf16_f32 v0, v0, s0
	ds_write_b16 v48, v0 offset:52288
	v_mul_f32_e32 v0, v5, v45
	v_cvt_pk_bf16_f32 v0, v0, s0
	ds_write_b16 v48, v0 offset:52352
	v_mul_f32_e32 v0, v21, v45
	v_cvt_pk_bf16_f32 v0, v0, s0
	ds_write_b16 v48, v0 offset:52416
	v_mul_f32_e32 v0, v6, v46
	v_cvt_pk_bf16_f32 v0, v0, s0
	ds_write_b16 v48, v0 offset:52480
	v_mul_f32_e32 v0, v22, v46
	v_cvt_pk_bf16_f32 v0, v0, s0
	s_waitcnt lgkmcnt(14)
; __device__ __forceinline__ int crow(int r,int hi){return (r&3)+8*(r>>2)+4*hi;}
; template<int THRL> __device__ __forceinline__ void attn_unit(long rowbase,int NT,int q0,const bf16*Qh,const bf16*Kc,const bf16*Vc,bf16*Oh,char*shm,const float*rope,const float*qn){
;     ...
;   { bf16*stg=(bf16*)(shm+LDS_OST)+wid*2048;
;     #pragma unroll
;     for(int r=0;r<16;++r){const int orow=crow(r,hi);
;       #pragma unroll
;       for(int d0=0;d0<2;++d0)stg[orow*64+d0*32+r32]=__float2bfloat16(o[d0][r]*rli[r]);}
;     asm volatile("s_waitcnt lgkmcnt(0)":::"memory");
;     #pragma unroll
;     for(int i=0;i<4;++i){const int row=i*8+(lane>>3),ch=lane&7; const u32x4 v=*(const u32x4*)(stg+row*64+ch*8); ATTN_STORE16(Ow+(long)row*PO+ch*8,v);} }
;   asm volatile("s_waitcnt lgkmcnt(0)\n\ts_barrier":::"memory");
; __device__ __forceinline__ void conv_mix_unit(const bf16_t* Z, bf16_t* mix, const float* E2, const float* cw, const float* cbias, long row0, int h, int t0, int S, int tid) {
;     const int pm = (int)(row0 >> 8);
; #pragma unroll
;     for (int it = 0; it < 4; ++it) {
;         const int idx = tid + 512 * it, r = idx >> 3, ch = h * 64 + (idx & 7) * 8; const size_t row = (size_t)row0 + r;
;         float fb[8], cp[8];
;         unpack8(*(const u32x4*)(Z + row * INW + 768 + ch), fb);
;         if (r == 0 || r == 255) {
;             const float* Ep = E2 + (size_t)pm * 4 * 512 + ch; const bool last = r == 255;
;             const float* r0 = last ? Ep + 2 * 512 : Ep - 512; const float* r1 = last ? Ep + 3 * 512 : Ep; const float* r2 = last ? Ep + 4 * 512 : Ep + 512;
;             const bool hasp = t0 + r > 0, hasn = t0 + r < S - 1;
; #pragma unroll
;             for (int i = 0; i < 8; ++i) cp[i] = cw[ch + i] * (hasp ? r0[i] : 0.f) + cw[512 + ch + i] * r1[i] + cw[1024 + ch + i] * (hasn ? r2[i] : 0.f) + cbias[ch + i];
;         } else unpack8(*(const u32x4*)(Z + row * INW + 1280 + ch), cp);
	v_rcp_f32_e32 v32, v32
	ds_write_b16 v48, v0 offset:52544
	v_mul_f32_e32 v0, v7, v47
	v_cvt_pk_bf16_f32 v0, v0, s0
	ds_write_b16 v48, v0 offset:52608
	v_mul_f32_e32 v0, v23, v47
	v_cvt_pk_bf16_f32 v0, v0, s0
	v_rcp_f32_e32 v33, v33
	ds_write_b16 v48, v0 offset:52672
	v_mul_f32_e32 v0, v8, v32
	v_cvt_pk_bf16_f32 v0, v0, s0
	ds_write_b16 v48, v0 offset:53248
	v_mul_f32_e32 v0, v24, v32
	v_cvt_pk_bf16_f32 v0, v0, s0
	v_rcp_f32_e32 v34, v34
	ds_write_b16 v48, v0 offset:53312
	v_mul_f32_e32 v0, v9, v33
	v_cvt_pk_bf16_f32 v0, v0, s0
	ds_write_b16 v48, v0 offset:53376
	v_mul_f32_e32 v0, v25, v33
	v_cvt_pk_bf16_f32 v0, v0, s0
	v_rcp_f32_e32 v35, v35
	ds_write_b16 v48, v0 offset:53440
	v_mul_f32_e32 v0, v10, v34
	v_cvt_pk_bf16_f32 v0, v0, s0
	ds_write_b16 v48, v0 offset:53504
	v_mul_f32_e32 v0, v26, v34
	v_cvt_pk_bf16_f32 v0, v0, s0
	s_waitcnt lgkmcnt(14)
	v_rcp_f32_e32 v36, v36
	ds_write_b16 v48, v0 offset:53568
	v_mul_f32_e32 v0, v11, v35
	v_cvt_pk_bf16_f32 v0, v0, s0
	ds_write_b16 v48, v0 offset:53632
	v_mul_f32_e32 v0, v27, v35
	v_cvt_pk_bf16_f32 v0, v0, s0
	v_rcp_f32_e32 v37, v37
	ds_write_b16 v48, v0 offset:53696
	v_mul_f32_e32 v0, v12, v36
	v_cvt_pk_bf16_f32 v0, v0, s0
	ds_write_b16 v48, v0 offset:54272
	v_mul_f32_e32 v0, v28, v36
	v_cvt_pk_bf16_f32 v0, v0, s0
	v_rcp_f32_e32 v38, v38
	ds_write_b16 v48, v0 offset:54336
	v_mul_f32_e32 v0, v13, v37
	v_cvt_pk_bf16_f32 v0, v0, s0
	ds_write_b16 v48, v0 offset:54400
	v_mul_f32_e32 v0, v29, v37
	v_cvt_pk_bf16_f32 v0, v0, s0
	v_rcp_f32_e32 v39, v39
	ds_write_b16 v48, v0 offset:54464
	v_mul_f32_e32 v0, v14, v38
	v_cvt_pk_bf16_f32 v0, v0, s0
	ds_write_b16 v48, v0 offset:54528
	v_mul_f32_e32 v0, v30, v38
	v_cvt_pk_bf16_f32 v0, v0, s0
	ds_write_b16 v48, v0 offset:54592
	v_mul_f32_e32 v0, v15, v39
	v_cvt_pk_bf16_f32 v0, v0, s0
	ds_write_b16 v48, v0 offset:54656
	v_mul_f32_e32 v0, v31, v39
	v_cvt_pk_bf16_f32 v0, v0, s0
	ds_write_b16 v48, v0 offset:54720
	v_lshlrev_b32_e32 v0, 1, v244
	v_and_b32_e32 v188, 0x70, v0
	v_lshrrev_b32_e32 v12, 3, v243
	v_add_u32_e32 v13, s5, v188
	s_waitcnt lgkmcnt(0)
	v_lshl_add_u32 v0, v12, 7, v13
	v_or_b32_e32 v14, 8, v12
	s_lshl_b64 s[34:35], s[34:35], 11
	ds_read_b128 v[0:3], v0 offset:51200
	v_lshl_add_u32 v4, v14, 7, v13
	s_add_u32 s0, s0, s34
	ds_read_b128 v[4:7], v4 offset:51200
	s_addc_u32 s1, s1, s35
	v_lshl_add_u64 v[8:9], s[0:1], 0, v[188:189]
	v_lshlrev_b32_e32 v188, 11, v12
	v_lshl_add_u64 v[10:11], v[8:9], 0, v[188:189]
	v_lshlrev_b32_e32 v188, 11, v14
	s_waitcnt lgkmcnt(1)
	global_store_dwordx4 v[10:11], v[0:3], off
	v_lshl_add_u64 v[16:17], s[30:31], 0, v[194:195]
	s_nop 0
	v_lshl_add_u64 v[0:1], v[8:9], 0, v[188:189]
	s_waitcnt lgkmcnt(0)
	global_store_dwordx4 v[0:1], v[4:7], off
	s_nop 1
	v_or_b32_e32 v4, 16, v12
	v_lshl_add_u32 v0, v4, 7, v13
	v_or_b32_e32 v12, 24, v12
	ds_read_b128 v[0:3], v0 offset:51200
	v_lshlrev_b32_e32 v188, 11, v4
	v_lshl_add_u32 v4, v12, 7, v13
	ds_read_b128 v[4:7], v4 offset:51200
	v_lshl_add_u64 v[10:11], v[8:9], 0, v[188:189]
	v_lshlrev_b32_e32 v188, 11, v12
	s_waitcnt lgkmcnt(1)
	global_store_dwordx4 v[10:11], v[0:3], off
	s_nop 1
	v_lshl_add_u64 v[0:1], v[8:9], 0, v[188:189]
	s_waitcnt lgkmcnt(0)
	global_store_dwordx4 v[0:1], v[4:7], off
	v_mov_b64_e32 v[0:1], s[12:13]
	v_mad_u64_u32 v[0:1], s[0:1], v16, s33, v[0:1]
	v_mov_b32_e32 v2, v1
	v_or_b32_e32 v188, s4, v242
	v_mad_u64_u32 v[2:3], s[0:1], v17, s33, v[2:3]
	v_mov_b32_e32 v1, v2
	v_lshlrev_b32_e32 v2, 1, v188
	v_mov_b32_e32 v3, v189
	s_waitcnt lgkmcnt(0)
	s_barrier
	v_lshl_add_u64 v[12:13], v[0:1], 0, v[2:3]
	v_add_u32_e32 v134, s30, v194
	v_mov_b32_e32 v132, s12
	v_mov_b32_e32 v133, s13
	v_mad_u64_u32 v[132:133], s[100:101], v134, s33, v[132:133]
	v_lshl_add_u64 v[132:133], v[132:133], 0, v[2:3]
	global_load_dwordx4 v[96:99], v[132:133], off offset:1536
	global_load_dwordx4 v[100:103], v[132:133], off offset:2560
	v_add_u32_e32 v134, s30, v202
	v_mov_b32_e32 v132, s12
	v_mov_b32_e32 v133, s13
	v_mad_u64_u32 v[132:133], s[100:101], v134, s33, v[132:133]
	v_lshl_add_u64 v[132:133], v[132:133], 0, v[2:3]
	global_load_dwordx4 v[104:107], v[132:133], off offset:1536
	global_load_dwordx4 v[108:111], v[132:133], off offset:2560
	v_add_u32_e32 v134, s30, v210
	v_mov_b32_e32 v132, s12
	v_mov_b32_e32 v133, s13
	v_mad_u64_u32 v[132:133], s[100:101], v134, s33, v[132:133]
	v_lshl_add_u64 v[132:133], v[132:133], 0, v[2:3]
	global_load_dwordx4 v[116:119], v[132:133], off offset:1536
	global_load_dwordx4 v[120:123], v[132:133], off offset:2560
	v_add_u32_e32 v134, s30, v218
	v_mov_b32_e32 v132, s12
	v_mov_b32_e32 v133, s13
	v_mad_u64_u32 v[132:133], s[100:101], v134, s33, v[132:133]
	v_lshl_add_u64 v[132:133], v[132:133], 0, v[2:3]
	global_load_dwordx4 v[124:127], v[132:133], off offset:1536
	global_load_dwordx4 v[128:131], v[132:133], off offset:2560
	s_load_dwordx4 s[40:43], s[54:55], 0x28
	s_lshl_b64 s[0:1], s[46:47], 2
	s_waitcnt lgkmcnt(0)
	s_add_u32 s38, s40, s0
	s_addc_u32 s39, s41, s1
	s_lshl_b64 s[0:1], s[48:49], 2
	s_add_u32 s34, s42, s0
	s_addc_u32 s35, s43, s1
	s_and_saveexec_b64 s[0:1], s[22:23]
	s_xor_b64 s[4:5], exec, s[0:1]
	s_cbranch_execz .LBB0_363

; __device__ __forceinline__ unsigned pk(float lo, float hi) { return pg8::cvt_pk_bf16(lo, hi); }
; __device__ __forceinline__ void conv_mix_unit(const bf16_t* Z, bf16_t* mix, const float* E2, const float* cw, const float* cbias, long row0, int h, int t0, int S, int tid) {
;     ...
;         const int idx = tid + 512 * it, r = idx >> 3, ch = h * 64 + (idx & 7) * 8; const size_t row = (size_t)row0 + r;
;         float fb[8], cp[8];
;         unpack8(*(const u32x4*)(Z + row * INW + 768 + ch), fb);
;         if (r == 0 || r == 255) {
;             const float* Ep = E2 + (size_t)pm * 4 * 512 + ch; const bool last = r == 255;
;             const float* r0 = last ? Ep + 2 * 512 : Ep - 512; const float* r1 = last ? Ep + 3 * 512 : Ep; const float* r2 = last ? Ep + 4 * 512 : Ep + 512;
;             const bool hasp = t0 + r > 0, hasn = t0 + r < S - 1;
; #pragma unroll
;             for (int i = 0; i < 8; ++i) cp[i] = cw[ch + i] * (hasp ? r0[i] : 0.f) + cw[512 + ch + i] * r1[i] + cw[1024 + ch + i] * (hasn ? r2[i] : 0.f) + cbias[ch + i];
;         } else unpack8(*(const u32x4*)(Z + row * INW + 1280 + ch), cp);
;         u32x4 w; w.x = pk(fb[0] * cp[0], fb[1] * cp[1]); w.y = pk(fb[2] * cp[2], fb[3] * cp[3]); w.z = pk(fb[4] * cp[4], fb[5] * cp[5]); w.w = pk(fb[6] * cp[6], fb[7] * cp[7]);
;         *(u32x4*)(mix + row * DM + 512 + ch) = w;
.LBB0_397:
	s_or_b64 exec, exec, s[36:37]
	s_waitcnt vmcnt(0)
	s_and_saveexec_b64 s[100:101], s[22:23]
	v_lshlrev_b32_e32 v0, 16, v100
	v_and_b32_e32 v1, 0xffff0000, v100
	v_lshlrev_b32_e32 v2, 16, v101
	v_and_b32_e32 v3, 0xffff0000, v101
	v_lshlrev_b32_e32 v4, 16, v102
	v_and_b32_e32 v5, 0xffff0000, v102
	v_lshlrev_b32_e32 v6, 16, v103
	v_and_b32_e32 v7, 0xffff0000, v103
	s_or_b64 exec, exec, s[100:101]
	v_lshlrev_b32_e32 v18, 16, v96
	v_and_b32_e32 v8, 0xffff0000, v96
	v_lshlrev_b32_e32 v19, 16, v97
	v_and_b32_e32 v9, 0xffff0000, v97
	v_mul_f32_e32 v0, v0, v18
	v_mul_f32_e32 v1, v1, v8
	v_lshlrev_b32_e32 v20, 16, v98
	v_and_b32_e32 v10, 0xffff0000, v98
	v_cvt_pk_bf16_f32 v0, v0, v1
	v_mul_f32_e32 v1, v2, v19
	v_mul_f32_e32 v2, v3, v9
	v_lshlrev_b32_e32 v21, 16, v99
	v_and_b32_e32 v11, 0xffff0000, v99
	v_cvt_pk_bf16_f32 v1, v1, v2
	v_mul_f32_e32 v2, v4, v20
	v_mul_f32_e32 v3, v5, v10
	v_cvt_pk_bf16_f32 v2, v2, v3
	v_mul_f32_e32 v3, v6, v21
	v_mul_f32_e32 v4, v7, v11
	v_cvt_pk_bf16_f32 v3, v3, v4
	v_lshlrev_b64 v[4:5], 11, v[16:17]
	v_lshl_add_u64 v[4:5], s[14:15], 0, v[4:5]
	v_lshlrev_b32_e32 v16, 1, v188
	v_mov_b32_e32 v17, v189
	v_lshl_add_u64 v[4:5], v[4:5], 0, v[16:17]
	global_store_dwordx4 v[4:5], v[0:3], off offset:1024
	v_lshl_add_u64 v[18:19], s[30:31], 0, v[202:203]
	s_nop 0
	v_mov_b64_e32 v[0:1], s[12:13]
	v_mad_u64_u32 v[0:1], s[0:1], v18, s33, v[0:1]
	v_mov_b32_e32 v2, v1
	v_mad_u64_u32 v[2:3], s[0:1], v19, s33, v[2:3]
	v_mov_b32_e32 v1, v2
	v_lshl_add_u64 v[20:21], v[0:1], 0, v[16:17]
	s_and_saveexec_b64 s[0:1], s[24:25]
	s_xor_b64 s[4:5], exec, s[0:1]
	s_cbranch_execz .LBB0_399
	v_lshlrev_b32_e32 v0, 16, v108
	v_and_b32_e32 v1, 0xffff0000, v108
	v_lshlrev_b32_e32 v2, 16, v109
	v_and_b32_e32 v3, 0xffff0000, v109
	v_lshlrev_b32_e32 v4, 16, v110
	v_and_b32_e32 v5, 0xffff0000, v110
	v_lshlrev_b32_e32 v6, 16, v111
	v_and_b32_e32 v7, 0xffff0000, v111

; __device__ __forceinline__ unsigned pk(float lo, float hi) { return pg8::cvt_pk_bf16(lo, hi); }
; __device__ __forceinline__ void conv_mix_unit(const bf16_t* Z, bf16_t* mix, const float* E2, const float* cw, const float* cbias, long row0, int h, int t0, int S, int tid) {
;     ...
;         const int idx = tid + 512 * it, r = idx >> 3, ch = h * 64 + (idx & 7) * 8; const size_t row = (size_t)row0 + r;
;         float fb[8], cp[8];
;         unpack8(*(const u32x4*)(Z + row * INW + 768 + ch), fb);
;         if (r == 0 || r == 255) {
;             const float* Ep = E2 + (size_t)pm * 4 * 512 + ch; const bool last = r == 255;
;             const float* r0 = last ? Ep + 2 * 512 : Ep - 512; const float* r1 = last ? Ep + 3 * 512 : Ep; const float* r2 = last ? Ep + 4 * 512 : Ep + 512;
;             const bool hasp = t0 + r > 0, hasn = t0 + r < S - 1;
; #pragma unroll
;             for (int i = 0; i < 8; ++i) cp[i] = cw[ch + i] * (hasp ? r0[i] : 0.f) + cw[512 + ch + i] * r1[i] + cw[1024 + ch + i] * (hasn ? r2[i] : 0.f) + cbias[ch + i];
;         } else unpack8(*(const u32x4*)(Z + row * INW + 1280 + ch), cp);
;         u32x4 w; w.x = pk(fb[0] * cp[0], fb[1] * cp[1]); w.y = pk(fb[2] * cp[2], fb[3] * cp[3]); w.z = pk(fb[4] * cp[4], fb[5] * cp[5]); w.w = pk(fb[6] * cp[6], fb[7] * cp[7]);
;         *(u32x4*)(mix + row * DM + 512 + ch) = w;
.LBB0_433:
	s_or_b64 exec, exec, s[36:37]
	v_lshlrev_b32_e32 v17, 16, v104
	v_and_b32_e32 v8, 0xffff0000, v104
	v_lshlrev_b32_e32 v20, 16, v105
	v_and_b32_e32 v9, 0xffff0000, v105
	v_mul_f32_e32 v0, v0, v17
	v_mul_f32_e32 v1, v1, v8
	v_lshlrev_b32_e32 v21, 16, v106
	v_and_b32_e32 v10, 0xffff0000, v106
	v_cvt_pk_bf16_f32 v0, v0, v1
	v_mul_f32_e32 v1, v2, v20
	v_mul_f32_e32 v2, v3, v9
	v_lshlrev_b32_e32 v22, 16, v107
	v_and_b32_e32 v11, 0xffff0000, v107
	v_cvt_pk_bf16_f32 v1, v1, v2
	v_mul_f32_e32 v2, v4, v21
	v_mul_f32_e32 v3, v5, v10
	v_cvt_pk_bf16_f32 v2, v2, v3
	v_mul_f32_e32 v3, v6, v22
	v_mul_f32_e32 v4, v7, v11
	v_cvt_pk_bf16_f32 v3, v3, v4
	v_lshlrev_b64 v[4:5], 11, v[18:19]
	v_lshl_add_u64 v[4:5], s[14:15], 0, v[4:5]
	v_mov_b32_e32 v17, v189
	v_lshl_add_u64 v[4:5], v[4:5], 0, v[16:17]
	global_store_dwordx4 v[4:5], v[0:3], off offset:1024
	v_lshl_add_u64 v[18:19], s[30:31], 0, v[210:211]
	s_nop 0
	v_mov_b64_e32 v[0:1], s[12:13]
	v_mad_u64_u32 v[0:1], s[0:1], v18, s33, v[0:1]
	v_mov_b32_e32 v2, v1
	v_mad_u64_u32 v[2:3], s[0:1], v19, s33, v[2:3]
	v_mov_b32_e32 v1, v2
	v_lshl_add_u64 v[20:21], v[0:1], 0, v[16:17]
	s_and_saveexec_b64 s[0:1], s[26:27]
	s_xor_b64 s[4:5], exec, s[0:1]
	s_cbranch_execz .LBB0_435
	v_lshlrev_b32_e32 v0, 16, v120
	v_and_b32_e32 v1, 0xffff0000, v120
	v_lshlrev_b32_e32 v2, 16, v121
	v_and_b32_e32 v3, 0xffff0000, v121
	v_lshlrev_b32_e32 v4, 16, v122
	v_and_b32_e32 v5, 0xffff0000, v122
	v_lshlrev_b32_e32 v6, 16, v123
	v_and_b32_e32 v7, 0xffff0000, v123

; __device__ __forceinline__ unsigned pk(float lo, float hi) { return pg8::cvt_pk_bf16(lo, hi); }
; __device__ __forceinline__ void conv_mix_unit(const bf16_t* Z, bf16_t* mix, const float* E2, const float* cw, const float* cbias, long row0, int h, int t0, int S, int tid) {
;     ...
;         const int idx = tid + 512 * it, r = idx >> 3, ch = h * 64 + (idx & 7) * 8; const size_t row = (size_t)row0 + r;
;         float fb[8], cp[8];
;         unpack8(*(const u32x4*)(Z + row * INW + 768 + ch), fb);
;         if (r == 0 || r == 255) {
;             const float* Ep = E2 + (size_t)pm * 4 * 512 + ch; const bool last = r == 255;
;             const float* r0 = last ? Ep + 2 * 512 : Ep - 512; const float* r1 = last ? Ep + 3 * 512 : Ep; const float* r2 = last ? Ep + 4 * 512 : Ep + 512;
;             const bool hasp = t0 + r > 0, hasn = t0 + r < S - 1;
; #pragma unroll
;             for (int i = 0; i < 8; ++i) cp[i] = cw[ch + i] * (hasp ? r0[i] : 0.f) + cw[512 + ch + i] * r1[i] + cw[1024 + ch + i] * (hasn ? r2[i] : 0.f) + cbias[ch + i];
;         } else unpack8(*(const u32x4*)(Z + row * INW + 1280 + ch), cp);
;         u32x4 w; w.x = pk(fb[0] * cp[0], fb[1] * cp[1]); w.y = pk(fb[2] * cp[2], fb[3] * cp[3]); w.z = pk(fb[4] * cp[4], fb[5] * cp[5]); w.w = pk(fb[6] * cp[6], fb[7] * cp[7]);
;         *(u32x4*)(mix + row * DM + 512 + ch) = w;
.LBB0_469:
	s_or_b64 exec, exec, s[36:37]
	v_lshlrev_b32_e32 v17, 16, v116
	v_and_b32_e32 v8, 0xffff0000, v116
	v_lshlrev_b32_e32 v20, 16, v117
	v_and_b32_e32 v9, 0xffff0000, v117
	v_mul_f32_e32 v0, v0, v17
	v_mul_f32_e32 v1, v1, v8
	v_lshlrev_b32_e32 v21, 16, v118
	v_and_b32_e32 v10, 0xffff0000, v118
	v_cvt_pk_bf16_f32 v0, v0, v1
	v_mul_f32_e32 v1, v2, v20
	v_mul_f32_e32 v2, v3, v9
	v_lshlrev_b32_e32 v22, 16, v119
	v_and_b32_e32 v11, 0xffff0000, v119
	v_cvt_pk_bf16_f32 v1, v1, v2
	v_mul_f32_e32 v2, v4, v21
	v_mul_f32_e32 v3, v5, v10
	v_cvt_pk_bf16_f32 v2, v2, v3
	v_mul_f32_e32 v3, v6, v22
	v_mul_f32_e32 v4, v7, v11
	v_cvt_pk_bf16_f32 v3, v3, v4
	v_lshlrev_b64 v[4:5], 11, v[18:19]
	v_lshl_add_u64 v[4:5], s[14:15], 0, v[4:5]
	v_mov_b32_e32 v17, v189
	v_lshl_add_u64 v[4:5], v[4:5], 0, v[16:17]
	global_store_dwordx4 v[4:5], v[0:3], off offset:1024
	v_lshl_add_u64 v[18:19], s[30:31], 0, v[218:219]
	s_nop 0
	v_mov_b64_e32 v[0:1], s[12:13]
	v_mad_u64_u32 v[0:1], s[0:1], v18, s33, v[0:1]
	v_mov_b32_e32 v2, v1
	v_mad_u64_u32 v[2:3], s[0:1], v19, s33, v[2:3]
	v_mov_b32_e32 v1, v2
	v_lshl_add_u64 v[20:21], v[0:1], 0, v[16:17]
	s_and_saveexec_b64 s[0:1], s[28:29]
	s_xor_b64 s[4:5], exec, s[0:1]
	s_cbranch_execz .LBB0_471
	v_lshlrev_b32_e32 v0, 16, v128
	v_and_b32_e32 v1, 0xffff0000, v128
	v_lshlrev_b32_e32 v2, 16, v129
	v_and_b32_e32 v3, 0xffff0000, v129
	v_lshlrev_b32_e32 v4, 16, v130
	v_and_b32_e32 v5, 0xffff0000, v130
	v_lshlrev_b32_e32 v6, 16, v131
	v_and_b32_e32 v7, 0xffff0000, v131

; __global__ void __launch_bounds__(512, 2) mega_fwd(Args a_unused) {
;     extern __shared__ __attribute__((aligned(16))) unsigned char lds[];
;     cg::grid_group grid = cg::this_grid();
;     const __attribute__((address_space(4))) Args* kp = (const __attribute__((address_space(4))) Args*)__builtin_amdgcn_kernarg_segment_ptr();
	.amdhsa_kernel _ZN2mk8mega_fwdENS_4ArgsE
		.amdhsa_group_segment_fixed_size 0
		.amdhsa_private_segment_fixed_size 0
		.amdhsa_kernarg_size 400
		.amdhsa_user_sgpr_count 2
		.amdhsa_user_sgpr_dispatch_ptr 0
		.amdhsa_user_sgpr_queue_ptr 0
		.amdhsa_user_sgpr_kernarg_segment_ptr 1
		.amdhsa_user_sgpr_dispatch_id 0
		.amdhsa_user_sgpr_kernarg_preload_length 0
		.amdhsa_user_sgpr_kernarg_preload_offset 0
		.amdhsa_user_sgpr_private_segment_size 0
		.amdhsa_uses_dynamic_stack 0
		.amdhsa_enable_private_segment 0
		.amdhsa_system_sgpr_workgroup_id_x 1
		.amdhsa_system_sgpr_workgroup_id_y 0
		.amdhsa_system_sgpr_workgroup_id_z 0
		.amdhsa_system_sgpr_workgroup_info 0
		.amdhsa_system_vgpr_workitem_id 2
		.amdhsa_next_free_vgpr 256
		.amdhsa_next_free_sgpr 102
		.amdhsa_accum_offset 256
		.amdhsa_reserve_vcc 1
		.amdhsa_float_round_mode_32 0
		.amdhsa_float_round_mode_16_64 0
		.amdhsa_float_denorm_mode_32 3
		.amdhsa_float_denorm_mode_16_64 3
		.amdhsa_dx10_clamp 1
		.amdhsa_ieee_mode 1
		.amdhsa_fp16_overflow 0
		.amdhsa_tg_split 0
		.amdhsa_exception_fp_ieee_invalid_op 0
		.amdhsa_exception_fp_denorm_src 0
		.amdhsa_exception_fp_ieee_div_zero 0
		.amdhsa_exception_fp_ieee_overflow 0
		.amdhsa_exception_fp_ieee_underflow 0
		.amdhsa_exception_fp_ieee_inexact 0
		.amdhsa_exception_int_div_zero 0
	.end_amdhsa_kernel

; __global__ void __launch_bounds__(512, 2) mega_fwd(Args a_unused) {
;     extern __shared__ __attribute__((aligned(16))) unsigned char lds[];
;     cg::grid_group grid = cg::this_grid();
;     const __attribute__((address_space(4))) Args* kp = (const __attribute__((address_space(4))) Args*)__builtin_amdgcn_kernarg_segment_ptr();
amdhsa.kernels:
  - .agpr_count:     0
    .args:
      - .offset:         0
        .size:           144
        .value_kind:     by_value
      - .offset:         144
        .size:           4
        .value_kind:     hidden_block_count_x
      - .offset:         148
        .size:           4
        .value_kind:     hidden_block_count_y
      - .offset:         152
        .size:           4
        .value_kind:     hidden_block_count_z
      - .offset:         156
        .size:           2
        .value_kind:     hidden_group_size_x
      - .offset:         158
        .size:           2
        .value_kind:     hidden_group_size_y
      - .offset:         160
        .size:           2
        .value_kind:     hidden_group_size_z
      - .offset:         162
        .size:           2
        .value_kind:     hidden_remainder_x
      - .offset:         164
        .size:           2
        .value_kind:     hidden_remainder_y
      - .offset:         166
        .size:           2
        .value_kind:     hidden_remainder_z
      - .offset:         184
        .size:           8
        .value_kind:     hidden_global_offset_x
      - .offset:         192
        .size:           8
        .value_kind:     hidden_global_offset_y
      - .offset:         200
        .size:           8
        .value_kind:     hidden_global_offset_z
      - .offset:         208
        .size:           2
        .value_kind:     hidden_grid_dims
      - .offset:         232
        .size:           8
        .value_kind:     hidden_multigrid_sync_arg
      - .offset:         264
        .size:           4
        .value_kind:     hidden_dynamic_lds_size
    .group_segment_fixed_size: 0
    .kernarg_segment_align: 8
    .kernarg_segment_size: 400
    .language:       OpenCL C
    .language_version:
      - 2
      - 0
    .max_flat_workgroup_size: 512
    .name:           _ZN2mk8mega_fwdENS_4ArgsE
    .private_segment_fixed_size: 0
    .sgpr_count:     108
    .sgpr_spill_count: 118
    .symbol:         _ZN2mk8mega_fwdENS_4ArgsE.kd
    .uniform_work_group_size: 1
    .uses_dynamic_stack: false
    .vgpr_count:     256
    .vgpr_spill_count: 0
    .wavefront_size: 64
